# v57 + MLA steady step: first K-fragment read of the next tile issued right behind the end-of-step barrier, ahead of the exit branch
# speedup vs baseline: 1.0043x; 1.0007x over previous
.Lmla2_reads2:
	ds_read_b128 v[158:161], v67 offset:2048
	ds_read_b128 v[162:165], v66
	ds_read_b128 v[150:153], v66 offset:2048
	ds_read_b128 v[146:149], v67 offset:4096
	ds_read_b128 v[142:145], v67 offset:6144
	ds_read_b128 v[138:141], v66 offset:4096
	ds_read_b128 v[134:137], v66 offset:6144
	ds_read_b128 v[130:133], v67 offset:8192
	ds_read_b128 v[126:129], v67 offset:10240
	ds_read_b128 v[122:125], v66 offset:8192
	ds_read_b128 v[154:157], v66 offset:10240
	s_waitcnt lgkmcnt(11)
	v_mfma_f32_32x32x16_bf16 v[66:81], v[82:85], v[98:101], v[50:65]
	s_lshl_b32 s58, s49, 13
	s_waitcnt lgkmcnt(10)
	v_mfma_f32_32x32x16_bf16 v[82:97], v[158:161], v[98:101], v[50:65]
	v_add_u32_e32 v158, s58, v183
	s_add_u32 s26, s54, s24
	s_addc_u32 s27, s55, s25
	s_xor_b32 s57, s49, 1
	s_mul_i32 s56, s57, 0x3000
	s_add_i32 s51, s56, s38
	s_mov_b32 s98, m0
	s_mov_b32 m0, s51
	s_nop 0
	global_load_lds_dwordx4 v1, s[26:27]
	s_mov_b32 m0, s98
	s_and_b64 vcc, exec, s[8:9]
	s_cbranch_vccnz .LBB0_1478
	s_add_i32 s26, s56, s39
	s_mov_b32 s27, m0
	s_mov_b32 m0, s26
	s_nop 0
	global_load_lds_dwordx4 v180, s[22:23]
	s_mov_b32 m0, s27

.LBB0_1482:
	v_exp_f32_e32 v66, v66
	v_exp_f32_e32 v67, v67
	v_exp_f32_e32 v68, v68
	v_exp_f32_e32 v69, v69
	v_exp_f32_e32 v70, v70
	v_exp_f32_e32 v71, v71
	v_exp_f32_e32 v72, v72
	v_exp_f32_e32 v73, v73
	v_pk_add_f32 v[154:155], v[66:67], v[68:69]
	v_pk_add_f32 v[156:157], v[70:71], v[72:73]
	v_pk_add_f32 v[158:159], v[154:155], v[156:157]
	v_cvt_pk_bf16_f32 v66, v66, v67
	v_cvt_pk_bf16_f32 v67, v68, v69
	v_cvt_pk_bf16_f32 v68, v70, v71
	v_cvt_pk_bf16_f32 v69, v72, v73
	v_exp_f32_e32 v74, v74
	v_exp_f32_e32 v75, v75
	v_mfma_f32_32x32x16_bf16 v[18:33], v[66:69], v[150:153], v[18:33]
	v_exp_f32_e32 v76, v76
	v_exp_f32_e32 v77, v77
	v_exp_f32_e32 v78, v78
	s_waitcnt lgkmcnt(6)
	v_mfma_f32_32x32x16_bf16 v[34:49], v[66:69], v[134:137], v[34:49]
	v_exp_f32_e32 v79, v79
	v_exp_f32_e32 v80, v80
	v_exp_f32_e32 v81, v81
	v_pk_add_f32 v[154:155], v[74:75], v[76:77]
	v_pk_add_f32 v[156:157], v[78:79], v[80:81]
	v_pk_add_f32 v[160:161], v[154:155], v[156:157]
	v_cvt_pk_bf16_f32 v70, v74, v75
	v_cvt_pk_bf16_f32 v71, v76, v77
	v_cvt_pk_bf16_f32 v72, v78, v79
	v_cvt_pk_bf16_f32 v73, v80, v81
	v_exp_f32_e32 v82, v82
	v_exp_f32_e32 v83, v83
	v_mfma_f32_32x32x16_bf16 v[18:33], v[70:73], v[146:149], v[18:33]
	v_exp_f32_e32 v84, v84
	v_exp_f32_e32 v85, v85
	v_exp_f32_e32 v86, v86
	s_waitcnt lgkmcnt(4)
	v_mfma_f32_32x32x16_bf16 v[34:49], v[70:73], v[130:133], v[34:49]
	v_exp_f32_e32 v87, v87
	v_exp_f32_e32 v88, v88
	v_exp_f32_e32 v89, v89
	v_pk_add_f32 v[154:155], v[82:83], v[84:85]
	v_pk_add_f32 v[156:157], v[86:87], v[88:89]
	v_pk_add_f32 v[162:163], v[154:155], v[156:157]
	v_cvt_pk_bf16_f32 v74, v82, v83
	v_cvt_pk_bf16_f32 v75, v84, v85
	v_cvt_pk_bf16_f32 v76, v86, v87
	v_cvt_pk_bf16_f32 v77, v88, v89
	v_exp_f32_e32 v90, v90
	v_exp_f32_e32 v91, v91
	v_mfma_f32_32x32x16_bf16 v[18:33], v[74:77], v[142:145], v[18:33]
	v_exp_f32_e32 v92, v92
	v_exp_f32_e32 v93, v93
	v_exp_f32_e32 v94, v94
	s_waitcnt lgkmcnt(2)
	v_mfma_f32_32x32x16_bf16 v[34:49], v[74:77], v[126:129], v[34:49]
	v_exp_f32_e32 v95, v95
	v_exp_f32_e32 v96, v96
	v_exp_f32_e32 v97, v97
	v_pk_add_f32 v[154:155], v[90:91], v[92:93]
	v_pk_add_f32 v[156:157], v[94:95], v[96:97]
	v_pk_add_f32 v[164:165], v[154:155], v[156:157]
	v_cvt_pk_bf16_f32 v78, v90, v91
	v_cvt_pk_bf16_f32 v79, v92, v93
	v_cvt_pk_bf16_f32 v80, v94, v95
	v_cvt_pk_bf16_f32 v81, v96, v97
	v_pk_add_f32 v[158:159], v[158:159], v[160:161]
	s_add_u32 s24, s24, 0x10000
	s_addc_u32 s25, s25, 0
	v_mfma_f32_32x32x16_bf16 v[18:33], v[78:81], v[138:141], v[18:33]
	v_pk_add_f32 v[162:163], v[162:163], v[164:165]
	s_add_u32 s22, s22, 0x1000
	s_addc_u32 s23, s23, 0
	s_waitcnt lgkmcnt(0)
	v_mfma_f32_32x32x16_bf16 v[34:49], v[78:81], v[122:125], v[34:49]
	v_pk_add_f32 v[158:159], v[158:159], v[162:163]
	v_add_f32_e32 v158, v158, v159
	v_add_u32_e32 v66, s56, v182
	v_add_f32_e32 v173, v173, v158
	v_add_u32_e32 v67, v66, v184
	v_add_u32_e32 v66, v66, v189
	s_cmp_eq_u32 s24, 0x200000
	s_waitcnt vmcnt(0) lgkmcnt(0)
	s_barrier
	ds_read_b128 v[82:85], v67
	s_cbranch_scc1 .LBB0_1484
	s_mov_b32 s49, s57
	s_mul_i32 s52, s49, 0x3000
	s_branch .Lmla2_reads2
